# plus: loop-invariant LDS read base hoisted out of the K-loop
# speedup vs baseline: 1.0272x; 1.0010x over previous
; #define PG8_STAGE(bufoff, gbase, off, q) do { \
;         __builtin_amdgcn_global_load_lds((const unsigned*)((const char*)(gbase) + (off)), (LAS unsigned*)(lds + (bufoff) + ldsw), 16, 0, 0); \
;         __builtin_amdgcn_global_load_lds((const unsigned*)((const char*)(gbase) + (q) + (off)), (LAS unsigned*)(lds + (bufoff) + ldsw + 8192), 16, 0, 0); } while (0)
; #define PG8_LDA(dst, b, h) do { _Pragma("unroll") for (int m = 0; m < 4; ++m) _Pragma("unroll") for (int k = 0; k < 2; ++k) dst[m][k] = *(const LAS bf16x8*)(lds + PG8_SA(b, h) + aoff + m * 2048 + k * 1024); } while (0)
; #define PG8_LDB(dst, b, h) do { _Pragma("unroll") for (int n = 0; n < 2; ++n) _Pragma("unroll") for (int k = 0; k < 2; ++k) dst[n][k] = *(const LAS bf16x8*)(lds + PG8_SB(b, h) + boff + n * 2048 + k * 1024); } while (0)
; #define PG8_SCHED __builtin_amdgcn_sched_barrier(0)
; template <class Epi, class Sched>
; __device__ __forceinline__ void gemm_phase(LAS unsigned char* lds, const int tid, const Sched& S, const Epi& E) {
;     ...
;         const int nqA = 64 * nlda, nqB = 64 * nldb, nhA = 128 * nlda, nhB = 128 * nldb;
;         const int nt = cur.nt;
;         for (int t = 0; t < nt; t += 2) {
;             const bool last = (t == nt - 2);
;             const char* a1 = cA + (size_t)(t + 1) * kstep;
;             const char* a2 = last ? nA : cA + (size_t)(t + 2) * kstep; const char* b2 = last ? nB : cB + (size_t)(t + 2) * kstep;
;             const char* a3 = a2 + kstep; const char* b3 = b2 + kstep;
;             const unsigned oA2 = last ? noffA : offA, oB2 = last ? noffB : offB;
;             const int qA2 = last ? nqA : qA, qB2 = last ? nqB : qB, hA2 = last ? nhA : hA, hB2 = last ? nhB : hB;
;             PG8_LDB(B0, 0, 0); PG8_LDB(B1, 0, 1); PG8_SCHED; PG8_LDA(At, 0, 0); PG8_STAGE(PG8_SA(1, 1), a1 + hA, offA, qA);
;     ...
; #pragma unroll
;         for (int a = 0; a < 2; ++a)
; #pragma unroll
;             for (int b = 0; b < 2; ++b)
; #pragma unroll
;                 for (int m = 0; m < 4; ++m)
; #pragma unroll
;                     for (int n = 0; n < 2; ++n) acc[a][b][m][n] = (f32x4){0.f, 0.f, 0.f, 0.f};
.Lrc_join:
	v_mad_u64_u32 v[130:131], s[2:3], v2, s6, v[0:1]
	v_mad_u64_u32 v[132:133], s[2:3], v4, s7, v[0:1]
	s_lshl_b32 s2, s6, 6
	s_lshl_b32 s18, s7, 6
	s_lshl_b32 s84, s6, 7
	s_lshl_b32 s69, s7, 7
	s_cmp_lt_i32 s37, 1
	s_cbranch_scc1 .LBB0_178
	s_and_b64 s[6:7], s[60:61], exec
	s_cselect_b32 s82, s75, s41
	s_cselect_b32 s48, s74, s40
	s_cselect_b32 s15, s87, s43
	s_cselect_b32 s14, s86, s42
	s_add_i32 s49, s37, -2
	s_ashr_i32 s97, s96, 31
	s_mov_b32 s4, s68
	s_add_u32 s68, s40, s96
	s_addc_u32 s16, s41, s97
	v_mov_b32_e32 v135, v1
	s_ashr_i32 s67, s66, 31
	v_mov_b32_e32 v131, v1
	s_ashr_i32 s3, s2, 31
	s_ashr_i32 s85, s84, 31
	s_mov_b32 s17, 0
	v_add_u32_e32 v133, 0x10000, v147
	s_cmp_lt_u32 s89, 2
	s_cbranch_scc0 .Lk0_dispatch
	v_mov_b32_e32 v2, 0
	v_mov_b32_e32 v3, v2
	v_mov_b32_e32 v4, v2
	v_mov_b32_e32 v5, v2
	v_mov_b32_e32 v6, v2
	v_mov_b32_e32 v7, v2
	v_mov_b32_e32 v8, v2
	v_mov_b32_e32 v9, v2
	v_mov_b32_e32 v18, v2
	v_mov_b32_e32 v19, v2
	v_mov_b32_e32 v20, v2
	v_mov_b32_e32 v21, v2
	v_mov_b32_e32 v22, v2
	v_mov_b32_e32 v23, v2
	v_mov_b32_e32 v24, v2
	v_mov_b32_e32 v25, v2
	v_mov_b32_e32 v34, v2
	v_mov_b32_e32 v35, v2
	v_mov_b32_e32 v36, v2
	v_mov_b32_e32 v37, v2
	v_mov_b32_e32 v38, v2
	v_mov_b32_e32 v39, v2
	v_mov_b32_e32 v40, v2
	v_mov_b32_e32 v41, v2
	v_mov_b32_e32 v50, v2
	v_mov_b32_e32 v51, v2
	v_mov_b32_e32 v52, v2
	v_mov_b32_e32 v53, v2
	v_mov_b32_e32 v54, v2
	v_mov_b32_e32 v55, v2
	v_mov_b32_e32 v56, v2
	v_mov_b32_e32 v57, v2
	v_mov_b32_e32 v10, v2
	v_mov_b32_e32 v11, v2
	v_mov_b32_e32 v12, v2
	v_mov_b32_e32 v13, v2
	v_mov_b32_e32 v14, v2
	v_mov_b32_e32 v15, v2
	v_mov_b32_e32 v16, v2
	v_mov_b32_e32 v17, v2
	v_mov_b32_e32 v26, v2
	v_mov_b32_e32 v27, v2
	v_mov_b32_e32 v28, v2
	v_mov_b32_e32 v29, v2
	v_mov_b32_e32 v30, v2
	v_mov_b32_e32 v31, v2
	v_mov_b32_e32 v32, v2
	v_mov_b32_e32 v33, v2
	v_mov_b32_e32 v42, v2
	v_mov_b32_e32 v43, v2
	v_mov_b32_e32 v44, v2
	v_mov_b32_e32 v45, v2
	v_mov_b32_e32 v46, v2
	v_mov_b32_e32 v47, v2
	v_mov_b32_e32 v48, v2
	v_mov_b32_e32 v49, v2
	v_mov_b32_e32 v58, v2
	v_mov_b32_e32 v59, v2
	v_mov_b32_e32 v60, v2
	v_mov_b32_e32 v61, v2
	v_mov_b32_e32 v62, v2
	v_mov_b32_e32 v63, v2
	v_mov_b32_e32 v64, v2
	v_mov_b32_e32 v65, v2
	v_mov_b32_e32 v66, v2
	v_mov_b32_e32 v67, v2
	v_mov_b32_e32 v68, v2
	v_mov_b32_e32 v69, v2
	v_mov_b32_e32 v70, v2
	v_mov_b32_e32 v71, v2
	v_mov_b32_e32 v72, v2
	v_mov_b32_e32 v73, v2
	v_mov_b32_e32 v82, v2
	v_mov_b32_e32 v83, v2
	v_mov_b32_e32 v84, v2
	v_mov_b32_e32 v85, v2
	v_mov_b32_e32 v86, v2
	v_mov_b32_e32 v87, v2
	v_mov_b32_e32 v88, v2
	v_mov_b32_e32 v89, v2
	v_mov_b32_e32 v98, v2
	v_mov_b32_e32 v99, v2
	v_mov_b32_e32 v100, v2
	v_mov_b32_e32 v101, v2
	v_mov_b32_e32 v102, v2
	v_mov_b32_e32 v103, v2
	v_mov_b32_e32 v104, v2
	v_mov_b32_e32 v105, v2
	v_mov_b32_e32 v114, v2
	v_mov_b32_e32 v115, v2
	v_mov_b32_e32 v116, v2
	v_mov_b32_e32 v117, v2
	v_mov_b32_e32 v118, v2
	v_mov_b32_e32 v119, v2
	v_mov_b32_e32 v120, v2
	v_mov_b32_e32 v121, v2
	v_mov_b32_e32 v74, v2
	v_mov_b32_e32 v75, v2
	v_mov_b32_e32 v76, v2
	v_mov_b32_e32 v77, v2
	v_mov_b32_e32 v78, v2
	v_mov_b32_e32 v79, v2
	v_mov_b32_e32 v80, v2
	v_mov_b32_e32 v81, v2
	v_mov_b32_e32 v90, v2
	v_mov_b32_e32 v91, v2
	v_mov_b32_e32 v92, v2
	v_mov_b32_e32 v93, v2
	v_mov_b32_e32 v94, v2
	v_mov_b32_e32 v95, v2
	v_mov_b32_e32 v96, v2
	v_mov_b32_e32 v97, v2
	v_mov_b32_e32 v106, v2
	v_mov_b32_e32 v107, v2
	v_mov_b32_e32 v108, v2
	v_mov_b32_e32 v109, v2
	v_mov_b32_e32 v110, v2
	v_mov_b32_e32 v111, v2
	v_mov_b32_e32 v112, v2
	v_mov_b32_e32 v113, v2
	v_mov_b32_e32 v122, v2
	v_mov_b32_e32 v123, v2
	v_mov_b32_e32 v124, v2
	v_mov_b32_e32 v125, v2
	v_mov_b32_e32 v126, v2
	v_mov_b32_e32 v127, v2
	v_mov_b32_e32 v128, v2
	v_mov_b32_e32 v129, v2
	s_branch .LBB0_173

; #define PG8_STAGE(bufoff, gbase, off, q) do { \
;         __builtin_amdgcn_global_load_lds((const unsigned*)((const char*)(gbase) + (off)), (LAS unsigned*)(lds + (bufoff) + ldsw), 16, 0, 0); \
;         __builtin_amdgcn_global_load_lds((const unsigned*)((const char*)(gbase) + (q) + (off)), (LAS unsigned*)(lds + (bufoff) + ldsw + 8192), 16, 0, 0); } while (0)
; #define PG8_LDA(dst, b, h) do { _Pragma("unroll") for (int m = 0; m < 4; ++m) _Pragma("unroll") for (int k = 0; k < 2; ++k) dst[m][k] = *(const LAS bf16x8*)(lds + PG8_SA(b, h) + aoff + m * 2048 + k * 1024); } while (0)
; #define PG8_LDB(dst, b, h) do { _Pragma("unroll") for (int n = 0; n < 2; ++n) _Pragma("unroll") for (int k = 0; k < 2; ++k) dst[n][k] = *(const LAS bf16x8*)(lds + PG8_SB(b, h) + boff + n * 2048 + k * 1024); } while (0)
; #define PG8_MMA(ai, bj, At, Bt) do { __builtin_amdgcn_s_setprio(1); _Pragma("unroll") for (int m = 0; m < 4; ++m) _Pragma("unroll") for (int n = 0; n < 2; ++n) _Pragma("unroll") for (int k = 0; k < 2; ++k) \
;         acc[ai][bj][m][n] = __builtin_amdgcn_mfma_f32_16x16x32_bf16(Bt[n][k], At[m][k], acc[ai][bj][m][n], 0, 0, 0); __builtin_amdgcn_s_setprio(0); } while (0)
; #define PG8_WAIT_V(n) asm volatile("s_waitcnt vmcnt(" #n ")" ::: "memory")
; #define PG8_WAIT_L(n) asm volatile("s_waitcnt lgkmcnt(" #n ")" ::: "memory")
; #define PG8_BAR __builtin_amdgcn_s_barrier()
; #define PG8_SCHED __builtin_amdgcn_sched_barrier(0)
; template <class Epi, class Sched>
; __device__ __forceinline__ void gemm_phase(LAS unsigned char* lds, const int tid, const Sched& S, const Epi& E) {
;     ...
;             PG8_LDB(B0, 0, 0); PG8_LDB(B1, 0, 1); PG8_SCHED; PG8_LDA(At, 0, 0); PG8_STAGE(PG8_SA(1, 1), a1 + hA, offA, qA);
;             PG8_WAIT_V(8); PG8_WAIT_L(0); PG8_BAR; PG8_MMA(0, 0, At, B0); PG8_MMA(0, 1, At, B1); PG8_BAR; PG8_SCHED;
;             PG8_LDA(At, 0, 1); PG8_STAGE(PG8_SB(0, 0), b2, oB2, qB2); PG8_STAGE(PG8_SB(0, 1), b2 + hB2, oB2, qB2); PG8_STAGE(PG8_SA(0, 0), a2, oA2, qA2);
;             PG8_WAIT_V(8); PG8_WAIT_L(0); PG8_BAR; PG8_MMA(1, 0, At, B0); PG8_MMA(1, 1, At, B1); PG8_BAR; PG8_SCHED;
.LBB0_175:
	s_or_b32 vcc_lo, s17, 1
	s_mov_b32 vcc_hi, s21
	s_lshl_b64 s[10:11], vcc, 7
	s_add_u32 s17, s40, s6
	s_addc_u32 vcc_lo, s41, s7
	s_and_b64 s[6:7], exec, s[62:63]
	s_cselect_b32 vcc_hi, s82, vcc_lo
	s_cselect_b32 vcc_lo, s48, s17
	s_add_i32 s17, 0, 0x10000
	s_add_i32 s62, 0, 0x14000
	ds_read_b128 v[140:143], v133
	ds_read_b128 v[150:153], v133 offset:1024
	ds_read_b128 v[154:157], v133 offset:2048
	ds_read_b128 v[158:161], v133 offset:3072
	ds_read_b128 v[186:189], v133 offset:16384
	ds_read_b128 v[190:193], v133 offset:17408
	ds_read_b128 v[194:197], v133 offset:18432
	ds_read_b128 v[198:201], v133 offset:19456
	s_add_u32 s6, s68, s10
	s_addc_u32 s7, s16, s11
	s_add_i32 m0, s54, 0xc000
	ds_read_b128 v[202:205], v184
	ds_read_b128 v[206:209], v184 offset:1024
	ds_read_b128 v[210:213], v184 offset:2048
	ds_read_b128 v[214:217], v184 offset:3072
	ds_read_b128 v[218:221], v184 offset:4096
	ds_read_b128 v[222:225], v184 offset:5120
	ds_read_b128 v[226:229], v184 offset:6144
	ds_read_b128 v[230:233], v184 offset:7168
	global_load_lds_dwordx4 v134, s[6:7]
	s_add_u32 s6, s6, s66
	s_addc_u32 s7, s7, s67
	s_add_i32 m0, s54, 0xe000
	s_nop 0
	global_load_lds_dwordx4 v134, s[6:7]
	s_waitcnt vmcnt(8)
	s_waitcnt lgkmcnt(0)
	s_setprio 1
	s_barrier
	v_mfma_f32_16x16x32_bf16 v[126:129], v[140:143], v[202:205], v[126:129]
	v_mfma_f32_16x16x32_bf16 v[122:125], v[154:157], v[202:205], v[122:125]
	v_mfma_f32_16x16x32_bf16 v[110:113], v[140:143], v[210:213], v[110:113]
	v_mfma_f32_16x16x32_bf16 v[106:109], v[154:157], v[210:213], v[106:109]
	v_mfma_f32_16x16x32_bf16 v[94:97], v[140:143], v[218:221], v[94:97]
	v_mfma_f32_16x16x32_bf16 v[90:93], v[154:157], v[218:221], v[90:93]
	v_mfma_f32_16x16x32_bf16 v[78:81], v[140:143], v[226:229], v[78:81]
	v_mfma_f32_16x16x32_bf16 v[74:77], v[154:157], v[226:229], v[74:77]
	v_mfma_f32_16x16x32_bf16 v[126:129], v[150:153], v[206:209], v[126:129]
	v_mfma_f32_16x16x32_bf16 v[122:125], v[158:161], v[206:209], v[122:125]
	v_mfma_f32_16x16x32_bf16 v[110:113], v[150:153], v[214:217], v[110:113]
	v_mfma_f32_16x16x32_bf16 v[106:109], v[158:161], v[214:217], v[106:109]
	v_mfma_f32_16x16x32_bf16 v[94:97], v[150:153], v[222:225], v[94:97]
	v_mfma_f32_16x16x32_bf16 v[90:93], v[158:161], v[222:225], v[90:93]
	v_mfma_f32_16x16x32_bf16 v[78:81], v[150:153], v[230:233], v[78:81]
	v_mfma_f32_16x16x32_bf16 v[74:77], v[158:161], v[230:233], v[74:77]
	v_mfma_f32_16x16x32_bf16 v[118:121], v[186:189], v[202:205], v[118:121]
	v_mfma_f32_16x16x32_bf16 v[114:117], v[194:197], v[202:205], v[114:117]
	v_mfma_f32_16x16x32_bf16 v[102:105], v[186:189], v[210:213], v[102:105]
	v_mfma_f32_16x16x32_bf16 v[98:101], v[194:197], v[210:213], v[98:101]
	v_mfma_f32_16x16x32_bf16 v[86:89], v[186:189], v[218:221], v[86:89]
	v_mfma_f32_16x16x32_bf16 v[82:85], v[194:197], v[218:221], v[82:85]
	v_mfma_f32_16x16x32_bf16 v[70:73], v[186:189], v[226:229], v[70:73]
	v_mfma_f32_16x16x32_bf16 v[66:69], v[194:197], v[226:229], v[66:69]
	v_mfma_f32_16x16x32_bf16 v[118:121], v[190:193], v[206:209], v[118:121]
	v_mfma_f32_16x16x32_bf16 v[114:117], v[198:201], v[206:209], v[114:117]
	v_mfma_f32_16x16x32_bf16 v[102:105], v[190:193], v[214:217], v[102:105]
	v_mfma_f32_16x16x32_bf16 v[98:101], v[198:201], v[214:217], v[98:101]
	v_mfma_f32_16x16x32_bf16 v[86:89], v[190:193], v[222:225], v[86:89]
	v_mfma_f32_16x16x32_bf16 v[82:85], v[198:201], v[222:225], v[82:85]
	v_mfma_f32_16x16x32_bf16 v[70:73], v[190:193], v[230:233], v[70:73]
	v_mfma_f32_16x16x32_bf16 v[66:69], v[198:201], v[230:233], v[66:69]
	s_barrier
	s_setprio 0
	s_add_i32 s10, s17, s47
	s_ashr_i32 s11, s73, 31
	s_mov_b32 m0, s10
	s_add_u32 s6, s28, s73
	ds_read_b128 v[202:205], v184 offset:16384
	ds_read_b128 v[206:209], v184 offset:17408
	ds_read_b128 v[210:213], v184 offset:18432
	ds_read_b128 v[214:217], v184 offset:19456
	ds_read_b128 v[218:221], v184 offset:20480
	ds_read_b128 v[222:225], v184 offset:21504
	ds_read_b128 v[226:229], v184 offset:22528
	ds_read_b128 v[230:233], v184 offset:23552
	global_load_lds_dwordx4 v0, s[28:29]
	s_addc_u32 s7, s29, s11
	s_add_i32 m0, s10, 0x2000
	s_nop 0
	global_load_lds_dwordx4 v0, s[6:7]
	s_ashr_i32 s7, s19, 31
	s_add_u32 s6, s28, s19
	s_addc_u32 s7, s29, s7
	s_add_i32 s10, s62, s47
	s_mov_b32 m0, s10
	s_nop 0
	global_load_lds_dwordx4 v0, s[6:7]
	s_add_u32 s6, s6, s73
	s_addc_u32 s7, s7, s11
	s_add_i32 m0, s10, 0x2000
	s_nop 0
	global_load_lds_dwordx4 v0, s[6:7]
	s_add_u32 s6, vcc_lo, s64
	s_mov_b32 m0, s54
	s_addc_u32 s7, vcc_hi, s65
	global_load_lds_dwordx4 v136, vcc
	s_mov_b32 m0, s55
	s_nop 0
	global_load_lds_dwordx4 v136, s[6:7]
	s_waitcnt vmcnt(8)
	s_waitcnt lgkmcnt(0)
	s_setprio 1
	s_barrier
; #define PG8_STAGE(bufoff, gbase, off, q) do { \
;         __builtin_amdgcn_global_load_lds((const unsigned*)((const char*)(gbase) + (off)), (LAS unsigned*)(lds + (bufoff) + ldsw), 16, 0, 0); \
;         __builtin_amdgcn_global_load_lds((const unsigned*)((const char*)(gbase) + (q) + (off)), (LAS unsigned*)(lds + (bufoff) + ldsw + 8192), 16, 0, 0); } while (0)
; #define PG8_LDA(dst, b, h) do { _Pragma("unroll") for (int m = 0; m < 4; ++m) _Pragma("unroll") for (int k = 0; k < 2; ++k) dst[m][k] = *(const LAS bf16x8*)(lds + PG8_SA(b, h) + aoff + m * 2048 + k * 1024); } while (0)
; #define PG8_LDB(dst, b, h) do { _Pragma("unroll") for (int n = 0; n < 2; ++n) _Pragma("unroll") for (int k = 0; k < 2; ++k) dst[n][k] = *(const LAS bf16x8*)(lds + PG8_SB(b, h) + boff + n * 2048 + k * 1024); } while (0)
; #define PG8_MMA(ai, bj, At, Bt) do { __builtin_amdgcn_s_setprio(1); _Pragma("unroll") for (int m = 0; m < 4; ++m) _Pragma("unroll") for (int n = 0; n < 2; ++n) _Pragma("unroll") for (int k = 0; k < 2; ++k) \
;         acc[ai][bj][m][n] = __builtin_amdgcn_mfma_f32_16x16x32_bf16(Bt[n][k], At[m][k], acc[ai][bj][m][n], 0, 0, 0); __builtin_amdgcn_s_setprio(0); } while (0)
; #define PG8_WAIT_V(n) asm volatile("s_waitcnt vmcnt(" #n ")" ::: "memory")
; #define PG8_WAIT_L(n) asm volatile("s_waitcnt lgkmcnt(" #n ")" ::: "memory")
; #define PG8_BAR __builtin_amdgcn_s_barrier()
; #define PG8_SCHED __builtin_amdgcn_sched_barrier(0)
; template <class Epi, class Sched>
; __device__ __forceinline__ void gemm_phase(LAS unsigned char* lds, const int tid, const Sched& S, const Epi& E) {
;     ...
;             PG8_WAIT_V(8); PG8_WAIT_L(0); PG8_BAR; PG8_MMA(1, 0, At, B0); PG8_MMA(1, 1, At, B1); PG8_BAR; PG8_SCHED;
;             PG8_LDB(B0, 1, 0); PG8_LDB(B1, 1, 1); PG8_SCHED; PG8_LDA(At, 1, 0); PG8_STAGE(PG8_SA(0, 1), a2 + hA2, oA2, qA2);
;             PG8_WAIT_V(8); PG8_WAIT_L(0); PG8_BAR; PG8_MMA(0, 0, At, B0); PG8_MMA(0, 1, At, B1); PG8_BAR; PG8_SCHED;
;             PG8_LDA(At, 1, 1); PG8_STAGE(PG8_SB(1, 0), b3, oB2, qB2); PG8_STAGE(PG8_SB(1, 1), b3 + hB2, oB2, qB2); PG8_STAGE(PG8_SA(1, 0), a3, oA2, qA2);
	v_mfma_f32_16x16x32_bf16 v[62:65], v[140:143], v[202:205], v[62:65]
	v_mfma_f32_16x16x32_bf16 v[58:61], v[154:157], v[202:205], v[58:61]
	v_mfma_f32_16x16x32_bf16 v[46:49], v[140:143], v[210:213], v[46:49]
	v_mfma_f32_16x16x32_bf16 v[42:45], v[154:157], v[210:213], v[42:45]
	v_mfma_f32_16x16x32_bf16 v[30:33], v[140:143], v[218:221], v[30:33]
	v_mfma_f32_16x16x32_bf16 v[26:29], v[154:157], v[218:221], v[26:29]
	v_mfma_f32_16x16x32_bf16 v[14:17], v[140:143], v[226:229], v[14:17]
	v_mfma_f32_16x16x32_bf16 v[10:13], v[154:157], v[226:229], v[10:13]
	v_mfma_f32_16x16x32_bf16 v[62:65], v[150:153], v[206:209], v[62:65]
	v_mfma_f32_16x16x32_bf16 v[58:61], v[158:161], v[206:209], v[58:61]
	v_mfma_f32_16x16x32_bf16 v[46:49], v[150:153], v[214:217], v[46:49]
	v_mfma_f32_16x16x32_bf16 v[42:45], v[158:161], v[214:217], v[42:45]
	v_mfma_f32_16x16x32_bf16 v[30:33], v[150:153], v[222:225], v[30:33]
	v_mfma_f32_16x16x32_bf16 v[26:29], v[158:161], v[222:225], v[26:29]
	v_mfma_f32_16x16x32_bf16 v[14:17], v[150:153], v[230:233], v[14:17]
	v_mfma_f32_16x16x32_bf16 v[10:13], v[158:161], v[230:233], v[10:13]
	v_mfma_f32_16x16x32_bf16 v[54:57], v[186:189], v[202:205], v[54:57]
	v_mfma_f32_16x16x32_bf16 v[50:53], v[194:197], v[202:205], v[50:53]
	v_mfma_f32_16x16x32_bf16 v[38:41], v[186:189], v[210:213], v[38:41]
	v_mfma_f32_16x16x32_bf16 v[34:37], v[194:197], v[210:213], v[34:37]
	v_mfma_f32_16x16x32_bf16 v[22:25], v[186:189], v[218:221], v[22:25]
	v_mfma_f32_16x16x32_bf16 v[18:21], v[194:197], v[218:221], v[18:21]
	v_mfma_f32_16x16x32_bf16 v[6:9], v[186:189], v[226:229], v[6:9]
	v_mfma_f32_16x16x32_bf16 v[2:5], v[194:197], v[226:229], v[2:5]
	v_mfma_f32_16x16x32_bf16 v[54:57], v[190:193], v[206:209], v[54:57]
	v_mfma_f32_16x16x32_bf16 v[50:53], v[198:201], v[206:209], v[50:53]
	v_mfma_f32_16x16x32_bf16 v[38:41], v[190:193], v[214:217], v[38:41]
	v_mfma_f32_16x16x32_bf16 v[34:37], v[198:201], v[214:217], v[34:37]
	v_mfma_f32_16x16x32_bf16 v[22:25], v[190:193], v[222:225], v[22:25]
	v_mfma_f32_16x16x32_bf16 v[18:21], v[198:201], v[222:225], v[18:21]
	v_mfma_f32_16x16x32_bf16 v[6:9], v[190:193], v[230:233], v[6:9]
	v_mfma_f32_16x16x32_bf16 v[2:5], v[198:201], v[230:233], v[2:5]
	s_barrier
	s_setprio 0
	s_add_i32 s10, 0, 0x18000
	s_add_i32 s11, 0, 0x1c000
	ds_read_b128 v[140:143], v133 offset:32768
	ds_read_b128 v[150:153], v133 offset:33792
	ds_read_b128 v[154:157], v133 offset:34816
	ds_read_b128 v[158:161], v133 offset:35840
	ds_read_b128 v[186:189], v133 offset:49152
	ds_read_b128 v[190:193], v133 offset:50176
	ds_read_b128 v[194:197], v133 offset:51200
	ds_read_b128 v[198:201], v133 offset:52224
	s_add_u32 s6, vcc_lo, s58
	s_addc_u32 s7, vcc_hi, s59
	s_mov_b32 m0, s91
	ds_read_b128 v[202:205], v184 offset:32768
	ds_read_b128 v[206:209], v184 offset:33792
	ds_read_b128 v[210:213], v184 offset:34816
	ds_read_b128 v[214:217], v184 offset:35840
	ds_read_b128 v[218:221], v184 offset:36864
	ds_read_b128 v[222:225], v184 offset:37888
	ds_read_b128 v[226:229], v184 offset:38912
	ds_read_b128 v[230:233], v184 offset:39936
	global_load_lds_dwordx4 v136, s[6:7]
	s_add_u32 s6, s6, s64
	s_addc_u32 s7, s7, s65
	s_mov_b32 m0, s93
	s_nop 0
	global_load_lds_dwordx4 v136, s[6:7]
	s_waitcnt vmcnt(8)
	s_waitcnt lgkmcnt(0)
	s_setprio 1
	s_barrier
	v_mfma_f32_16x16x32_bf16 v[126:129], v[140:143], v[202:205], v[126:129]
	v_mfma_f32_16x16x32_bf16 v[122:125], v[154:157], v[202:205], v[122:125]
	v_mfma_f32_16x16x32_bf16 v[110:113], v[140:143], v[210:213], v[110:113]
	v_mfma_f32_16x16x32_bf16 v[106:109], v[154:157], v[210:213], v[106:109]
	v_mfma_f32_16x16x32_bf16 v[94:97], v[140:143], v[218:221], v[94:97]
	v_mfma_f32_16x16x32_bf16 v[90:93], v[154:157], v[218:221], v[90:93]
	v_mfma_f32_16x16x32_bf16 v[78:81], v[140:143], v[226:229], v[78:81]
	v_mfma_f32_16x16x32_bf16 v[74:77], v[154:157], v[226:229], v[74:77]
	v_mfma_f32_16x16x32_bf16 v[126:129], v[150:153], v[206:209], v[126:129]
	v_mfma_f32_16x16x32_bf16 v[122:125], v[158:161], v[206:209], v[122:125]
	v_mfma_f32_16x16x32_bf16 v[110:113], v[150:153], v[214:217], v[110:113]
	v_mfma_f32_16x16x32_bf16 v[106:109], v[158:161], v[214:217], v[106:109]
	v_mfma_f32_16x16x32_bf16 v[94:97], v[150:153], v[222:225], v[94:97]
	v_mfma_f32_16x16x32_bf16 v[90:93], v[158:161], v[222:225], v[90:93]
	v_mfma_f32_16x16x32_bf16 v[78:81], v[150:153], v[230:233], v[78:81]
	v_mfma_f32_16x16x32_bf16 v[74:77], v[158:161], v[230:233], v[74:77]
	v_mfma_f32_16x16x32_bf16 v[118:121], v[186:189], v[202:205], v[118:121]
	v_mfma_f32_16x16x32_bf16 v[114:117], v[194:197], v[202:205], v[114:117]
	v_mfma_f32_16x16x32_bf16 v[102:105], v[186:189], v[210:213], v[102:105]
	v_mfma_f32_16x16x32_bf16 v[98:101], v[194:197], v[210:213], v[98:101]
	v_mfma_f32_16x16x32_bf16 v[86:89], v[186:189], v[218:221], v[86:89]
	v_mfma_f32_16x16x32_bf16 v[82:85], v[194:197], v[218:221], v[82:85]
	v_mfma_f32_16x16x32_bf16 v[70:73], v[186:189], v[226:229], v[70:73]
	v_mfma_f32_16x16x32_bf16 v[66:69], v[194:197], v[226:229], v[66:69]
	v_mfma_f32_16x16x32_bf16 v[118:121], v[190:193], v[206:209], v[118:121]
	v_mfma_f32_16x16x32_bf16 v[114:117], v[198:201], v[206:209], v[114:117]
	v_mfma_f32_16x16x32_bf16 v[102:105], v[190:193], v[214:217], v[102:105]
	v_mfma_f32_16x16x32_bf16 v[98:101], v[198:201], v[214:217], v[98:101]
	v_mfma_f32_16x16x32_bf16 v[86:89], v[190:193], v[222:225], v[86:89]
	v_mfma_f32_16x16x32_bf16 v[82:85], v[198:201], v[222:225], v[82:85]
	v_mfma_f32_16x16x32_bf16 v[70:73], v[190:193], v[230:233], v[70:73]
	v_mfma_f32_16x16x32_bf16 v[66:69], v[198:201], v[230:233], v[66:69]
	s_barrier
; #define PG8_STAGE(bufoff, gbase, off, q) do { \
;         __builtin_amdgcn_global_load_lds((const unsigned*)((const char*)(gbase) + (off)), (LAS unsigned*)(lds + (bufoff) + ldsw), 16, 0, 0); \
;         __builtin_amdgcn_global_load_lds((const unsigned*)((const char*)(gbase) + (q) + (off)), (LAS unsigned*)(lds + (bufoff) + ldsw + 8192), 16, 0, 0); } while (0)
; #define PG8_LDA(dst, b, h) do { _Pragma("unroll") for (int m = 0; m < 4; ++m) _Pragma("unroll") for (int k = 0; k < 2; ++k) dst[m][k] = *(const LAS bf16x8*)(lds + PG8_SA(b, h) + aoff + m * 2048 + k * 1024); } while (0)
; #define PG8_MMA(ai, bj, At, Bt) do { __builtin_amdgcn_s_setprio(1); _Pragma("unroll") for (int m = 0; m < 4; ++m) _Pragma("unroll") for (int n = 0; n < 2; ++n) _Pragma("unroll") for (int k = 0; k < 2; ++k) \
;         acc[ai][bj][m][n] = __builtin_amdgcn_mfma_f32_16x16x32_bf16(Bt[n][k], At[m][k], acc[ai][bj][m][n], 0, 0, 0); __builtin_amdgcn_s_setprio(0); } while (0)
; #define PG8_WAIT_V(n) asm volatile("s_waitcnt vmcnt(" #n ")" ::: "memory")
; #define PG8_WAIT_L(n) asm volatile("s_waitcnt lgkmcnt(" #n ")" ::: "memory")
; #define PG8_BAR __builtin_amdgcn_s_barrier()
; #define PG8_SCHED __builtin_amdgcn_sched_barrier(0)
; template <class Epi, class Sched>
; __device__ __forceinline__ void gemm_phase(LAS unsigned char* lds, const int tid, const Sched& S, const Epi& E) {
;     ...
;             PG8_LDA(At, 1, 1); PG8_STAGE(PG8_SB(1, 0), b3, oB2, qB2); PG8_STAGE(PG8_SB(1, 1), b3 + hB2, oB2, qB2); PG8_STAGE(PG8_SA(1, 0), a3, oA2, qA2);
;             PG8_WAIT_V(8); PG8_WAIT_L(0); PG8_BAR; PG8_MMA(1, 0, At, B0); PG8_MMA(1, 1, At, B1); PG8_BAR; PG8_SCHED;
;         }
	s_setprio 0
	s_add_i32 s6, s10, s47
	s_add_i32 m0, s6, 0xffffff80
	ds_read_b128 v[202:205], v184 offset:49152
	ds_read_b128 v[206:209], v184 offset:50176
	ds_read_b128 v[210:213], v184 offset:51200
	ds_read_b128 v[214:217], v184 offset:52224
	ds_read_b128 v[218:221], v184 offset:53248
	ds_read_b128 v[222:225], v184 offset:54272
	ds_read_b128 v[226:229], v184 offset:55296
	ds_read_b128 v[230:233], v184 offset:56320
	global_load_lds_dwordx4 v0, s[28:29] offset:128
	s_add_i32 m0, s6, 0x1f80
	s_add_i32 s6, s11, s47
	s_ashr_i32 s100, s73, 31
	s_add_u32 s98, s28, s73
	s_addc_u32 s99, s29, s100
	global_load_lds_dwordx4 v0, s[98:99] offset:128
	s_add_i32 m0, s6, 0xffffff80
	s_nop 0
	s_ashr_i32 s101, s19, 31
	s_add_u32 s98, s28, s19
	s_addc_u32 s99, s29, s101
	global_load_lds_dwordx4 v0, s[98:99] offset:128
	s_add_i32 m0, s6, 0x1f80
	s_nop 0
	s_add_u32 s98, s98, s73
	s_addc_u32 s99, s99, s100
	global_load_lds_dwordx4 v0, s[98:99] offset:128
	s_add_i32 m0, s77, 0xffffff80
	s_nop 0
	global_load_lds_dwordx4 v136, vcc offset:128
	s_add_i32 m0, s88, 0xffffff80
	s_nop 0
	s_add_u32 s98, vcc_lo, s64
	s_addc_u32 s99, vcc_hi, s65
	global_load_lds_dwordx4 v136, s[98:99] offset:128
	s_waitcnt vmcnt(8)
	s_waitcnt lgkmcnt(0)
	s_setprio 1
	s_barrier
	v_mfma_f32_16x16x32_bf16 v[62:65], v[140:143], v[202:205], v[62:65]
	v_mfma_f32_16x16x32_bf16 v[58:61], v[154:157], v[202:205], v[58:61]
	v_mfma_f32_16x16x32_bf16 v[46:49], v[140:143], v[210:213], v[46:49]
	v_mfma_f32_16x16x32_bf16 v[42:45], v[154:157], v[210:213], v[42:45]
	v_mfma_f32_16x16x32_bf16 v[30:33], v[140:143], v[218:221], v[30:33]
	v_mfma_f32_16x16x32_bf16 v[26:29], v[154:157], v[218:221], v[26:29]
	v_mfma_f32_16x16x32_bf16 v[14:17], v[140:143], v[226:229], v[14:17]
	v_mfma_f32_16x16x32_bf16 v[10:13], v[154:157], v[226:229], v[10:13]
	v_mfma_f32_16x16x32_bf16 v[62:65], v[150:153], v[206:209], v[62:65]
	v_mfma_f32_16x16x32_bf16 v[58:61], v[158:161], v[206:209], v[58:61]
	v_mfma_f32_16x16x32_bf16 v[46:49], v[150:153], v[214:217], v[46:49]
	v_mfma_f32_16x16x32_bf16 v[42:45], v[158:161], v[214:217], v[42:45]
	v_mfma_f32_16x16x32_bf16 v[30:33], v[150:153], v[222:225], v[30:33]
	v_mfma_f32_16x16x32_bf16 v[26:29], v[158:161], v[222:225], v[26:29]
	v_mfma_f32_16x16x32_bf16 v[14:17], v[150:153], v[230:233], v[14:17]
	v_mfma_f32_16x16x32_bf16 v[10:13], v[158:161], v[230:233], v[10:13]
	v_mfma_f32_16x16x32_bf16 v[54:57], v[186:189], v[202:205], v[54:57]
	v_mfma_f32_16x16x32_bf16 v[50:53], v[194:197], v[202:205], v[50:53]
	v_mfma_f32_16x16x32_bf16 v[38:41], v[186:189], v[210:213], v[38:41]
	v_mfma_f32_16x16x32_bf16 v[34:37], v[194:197], v[210:213], v[34:37]
	v_mfma_f32_16x16x32_bf16 v[22:25], v[186:189], v[218:221], v[22:25]
	v_mfma_f32_16x16x32_bf16 v[18:21], v[194:197], v[218:221], v[18:21]
	v_mfma_f32_16x16x32_bf16 v[6:9], v[186:189], v[226:229], v[6:9]
	v_mfma_f32_16x16x32_bf16 v[2:5], v[194:197], v[226:229], v[2:5]
	v_mfma_f32_16x16x32_bf16 v[54:57], v[190:193], v[206:209], v[54:57]
	v_mfma_f32_16x16x32_bf16 v[50:53], v[198:201], v[206:209], v[50:53]
	v_mfma_f32_16x16x32_bf16 v[38:41], v[190:193], v[214:217], v[38:41]
	v_mfma_f32_16x16x32_bf16 v[34:37], v[198:201], v[214:217], v[34:37]
	v_mfma_f32_16x16x32_bf16 v[22:25], v[190:193], v[222:225], v[22:25]
	v_mfma_f32_16x16x32_bf16 v[18:21], v[198:201], v[222:225], v[18:21]
	v_mfma_f32_16x16x32_bf16 v[6:9], v[190:193], v[230:233], v[6:9]
	v_mfma_f32_16x16x32_bf16 v[2:5], v[198:201], v[230:233], v[2:5]
	s_barrier
	s_setprio 0
	s_cmp_ge_i32 s20, s37
	s_cbranch_scc1 .LBB0_177
	s_mov_b32 s17, s20
	s_branch .LBB0_173

; #define PG8_STAGE(bufoff, gbase, off, q) do { \
;         __builtin_amdgcn_global_load_lds((const unsigned*)((const char*)(gbase) + (off)), (LAS unsigned*)(lds + (bufoff) + ldsw), 16, 0, 0); \
;         __builtin_amdgcn_global_load_lds((const unsigned*)((const char*)(gbase) + (q) + (off)), (LAS unsigned*)(lds + (bufoff) + ldsw + 8192), 16, 0, 0); } while (0)
; #define PG8_LDA(dst, b, h) do { _Pragma("unroll") for (int m = 0; m < 4; ++m) _Pragma("unroll") for (int k = 0; k < 2; ++k) dst[m][k] = *(const LAS bf16x8*)(lds + PG8_SA(b, h) + aoff + m * 2048 + k * 1024); } while (0)
; #define PG8_LDB(dst, b, h) do { _Pragma("unroll") for (int n = 0; n < 2; ++n) _Pragma("unroll") for (int k = 0; k < 2; ++k) dst[n][k] = *(const LAS bf16x8*)(lds + PG8_SB(b, h) + boff + n * 2048 + k * 1024); } while (0)
; #define PG8_MMA(ai, bj, At, Bt) do { __builtin_amdgcn_s_setprio(1); _Pragma("unroll") for (int m = 0; m < 4; ++m) _Pragma("unroll") for (int n = 0; n < 2; ++n) _Pragma("unroll") for (int k = 0; k < 2; ++k) \
;         acc[ai][bj][m][n] = __builtin_amdgcn_mfma_f32_16x16x32_bf16(Bt[n][k], At[m][k], acc[ai][bj][m][n], 0, 0, 0); __builtin_amdgcn_s_setprio(0); } while (0)
; #define PG8_WAIT_V(n) asm volatile("s_waitcnt vmcnt(" #n ")" ::: "memory")
; #define PG8_WAIT_L(n) asm volatile("s_waitcnt lgkmcnt(" #n ")" ::: "memory")
; #define PG8_BAR __builtin_amdgcn_s_barrier()
; #define PG8_SCHED __builtin_amdgcn_sched_barrier(0)
; template <class Epi, class Sched>
; __device__ __forceinline__ void gemm_phase(LAS unsigned char* lds, const int tid, const Sched& S, const Epi& E) {
;     ...
;             PG8_LDB(B0, 0, 0); PG8_LDB(B1, 0, 1); PG8_SCHED; PG8_LDA(At, 0, 0); PG8_STAGE(PG8_SA(1, 1), a1 + hA, offA, qA);
;             PG8_WAIT_V(8); PG8_WAIT_L(0); PG8_BAR; PG8_MMA(0, 0, At, B0); PG8_MMA(0, 1, At, B1); PG8_BAR; PG8_SCHED;
;             PG8_LDA(At, 0, 1); PG8_STAGE(PG8_SB(0, 0), b2, oB2, qB2); PG8_STAGE(PG8_SB(0, 1), b2 + hB2, oB2, qB2); PG8_STAGE(PG8_SA(0, 0), a2, oA2, qA2);
;             PG8_WAIT_V(8); PG8_WAIT_L(0); PG8_BAR; PG8_MMA(1, 0, At, B0); PG8_MMA(1, 1, At, B1); PG8_BAR; PG8_SCHED;
.Lk0a_175:
	s_or_b32 vcc_lo, s17, 1
	s_mov_b32 vcc_hi, s21
	s_lshl_b64 s[10:11], vcc, 7
	s_add_u32 s17, s40, s6
	s_addc_u32 vcc_lo, s41, s7
	s_and_b64 s[6:7], exec, s[62:63]
	s_cselect_b32 vcc_hi, s82, vcc_lo
	s_cselect_b32 vcc_lo, s48, s17
	s_add_i32 s17, 0, 0x10000
	s_add_i32 s62, 0, 0x14000
	ds_read_b128 v[140:143], v133
	ds_read_b128 v[150:153], v133 offset:1024
	ds_read_b128 v[154:157], v133 offset:2048
	ds_read_b128 v[158:161], v133 offset:3072
	ds_read_b128 v[186:189], v133 offset:16384
	ds_read_b128 v[190:193], v133 offset:17408
	ds_read_b128 v[194:197], v133 offset:18432
	ds_read_b128 v[198:201], v133 offset:19456
	s_add_u32 s6, s68, s10
	s_addc_u32 s7, s16, s11
	s_add_i32 m0, s54, 0xc000
	ds_read_b128 v[202:205], v184
	ds_read_b128 v[206:209], v184 offset:1024
	ds_read_b128 v[210:213], v184 offset:2048
	ds_read_b128 v[214:217], v184 offset:3072
	ds_read_b128 v[218:221], v184 offset:4096
	ds_read_b128 v[222:225], v184 offset:5120
	ds_read_b128 v[226:229], v184 offset:6144
	ds_read_b128 v[230:233], v184 offset:7168
	global_load_lds_dwordx4 v134, s[6:7]
	s_add_u32 s6, s6, s66
	s_addc_u32 s7, s7, s67
	s_add_i32 m0, s54, 0xe000
	s_nop 0
	global_load_lds_dwordx4 v134, s[6:7]
	s_waitcnt vmcnt(16)
	s_waitcnt lgkmcnt(0)
	s_setprio 1
	s_barrier
	v_mfma_f32_16x16x32_bf16 v[126:129], v[140:143], v[202:205], 0
	v_mfma_f32_16x16x32_bf16 v[122:125], v[154:157], v[202:205], 0
	v_mfma_f32_16x16x32_bf16 v[110:113], v[140:143], v[210:213], 0
	v_mfma_f32_16x16x32_bf16 v[106:109], v[154:157], v[210:213], 0
	v_mfma_f32_16x16x32_bf16 v[94:97], v[140:143], v[218:221], 0
	v_mfma_f32_16x16x32_bf16 v[90:93], v[154:157], v[218:221], 0
	v_mfma_f32_16x16x32_bf16 v[78:81], v[140:143], v[226:229], 0
	v_mfma_f32_16x16x32_bf16 v[74:77], v[154:157], v[226:229], 0
	v_mfma_f32_16x16x32_bf16 v[126:129], v[150:153], v[206:209], v[126:129]
	v_mfma_f32_16x16x32_bf16 v[122:125], v[158:161], v[206:209], v[122:125]
	v_mfma_f32_16x16x32_bf16 v[110:113], v[150:153], v[214:217], v[110:113]
	v_mfma_f32_16x16x32_bf16 v[106:109], v[158:161], v[214:217], v[106:109]
	v_mfma_f32_16x16x32_bf16 v[94:97], v[150:153], v[222:225], v[94:97]
	v_mfma_f32_16x16x32_bf16 v[90:93], v[158:161], v[222:225], v[90:93]
	v_mfma_f32_16x16x32_bf16 v[78:81], v[150:153], v[230:233], v[78:81]
	v_mfma_f32_16x16x32_bf16 v[74:77], v[158:161], v[230:233], v[74:77]
	v_mfma_f32_16x16x32_bf16 v[118:121], v[186:189], v[202:205], 0
	v_mfma_f32_16x16x32_bf16 v[114:117], v[194:197], v[202:205], 0
	v_mfma_f32_16x16x32_bf16 v[102:105], v[186:189], v[210:213], 0
	v_mfma_f32_16x16x32_bf16 v[98:101], v[194:197], v[210:213], 0
	v_mfma_f32_16x16x32_bf16 v[86:89], v[186:189], v[218:221], 0
	v_mfma_f32_16x16x32_bf16 v[82:85], v[194:197], v[218:221], 0
	v_mfma_f32_16x16x32_bf16 v[70:73], v[186:189], v[226:229], 0
	v_mfma_f32_16x16x32_bf16 v[66:69], v[194:197], v[226:229], 0
	v_mfma_f32_16x16x32_bf16 v[118:121], v[190:193], v[206:209], v[118:121]
	v_mfma_f32_16x16x32_bf16 v[114:117], v[198:201], v[206:209], v[114:117]
	v_mfma_f32_16x16x32_bf16 v[102:105], v[190:193], v[214:217], v[102:105]
	v_mfma_f32_16x16x32_bf16 v[98:101], v[198:201], v[214:217], v[98:101]
	v_mfma_f32_16x16x32_bf16 v[86:89], v[190:193], v[222:225], v[86:89]
	v_mfma_f32_16x16x32_bf16 v[82:85], v[198:201], v[222:225], v[82:85]
	v_mfma_f32_16x16x32_bf16 v[70:73], v[190:193], v[230:233], v[70:73]
	v_mfma_f32_16x16x32_bf16 v[66:69], v[198:201], v[230:233], v[66:69]
	s_barrier
	s_setprio 0
	s_add_i32 s10, s17, s47
	s_ashr_i32 s11, s73, 31
	s_mov_b32 m0, s10
	s_add_u32 s6, s28, s73
	ds_read_b128 v[202:205], v184 offset:16384
	ds_read_b128 v[206:209], v184 offset:17408
	ds_read_b128 v[210:213], v184 offset:18432
	ds_read_b128 v[214:217], v184 offset:19456
	ds_read_b128 v[218:221], v184 offset:20480
	ds_read_b128 v[222:225], v184 offset:21504
	ds_read_b128 v[226:229], v184 offset:22528
	ds_read_b128 v[230:233], v184 offset:23552
	global_load_lds_dwordx4 v0, s[28:29]
	s_addc_u32 s7, s29, s11
	s_add_i32 m0, s10, 0x2000
	s_nop 0
	global_load_lds_dwordx4 v0, s[6:7]
	s_ashr_i32 s7, s19, 31
	s_add_u32 s6, s28, s19
	s_addc_u32 s7, s29, s7
	s_add_i32 s10, s62, s47
	s_mov_b32 m0, s10
	s_nop 0
	global_load_lds_dwordx4 v0, s[6:7]
	s_add_u32 s6, s6, s73
	s_addc_u32 s7, s7, s11
	s_add_i32 m0, s10, 0x2000
	s_nop 0
	global_load_lds_dwordx4 v0, s[6:7]
	s_add_u32 s6, vcc_lo, s64
	s_mov_b32 m0, s54
	s_addc_u32 s7, vcc_hi, s65
	global_load_lds_dwordx4 v136, vcc
	s_mov_b32 m0, s55
	s_nop 0
	global_load_lds_dwordx4 v136, s[6:7]
	s_waitcnt vmcnt(16)
	s_waitcnt lgkmcnt(0)
	s_setprio 1
	s_barrier
	v_mfma_f32_16x16x32_bf16 v[62:65], v[140:143], v[202:205], 0
	v_mfma_f32_16x16x32_bf16 v[58:61], v[154:157], v[202:205], 0
	v_mfma_f32_16x16x32_bf16 v[46:49], v[140:143], v[210:213], 0
	v_mfma_f32_16x16x32_bf16 v[42:45], v[154:157], v[210:213], 0
	v_mfma_f32_16x16x32_bf16 v[30:33], v[140:143], v[218:221], 0
	v_mfma_f32_16x16x32_bf16 v[26:29], v[154:157], v[218:221], 0
	v_mfma_f32_16x16x32_bf16 v[14:17], v[140:143], v[226:229], 0
	v_mfma_f32_16x16x32_bf16 v[10:13], v[154:157], v[226:229], 0
	v_mfma_f32_16x16x32_bf16 v[62:65], v[150:153], v[206:209], v[62:65]
	v_mfma_f32_16x16x32_bf16 v[58:61], v[158:161], v[206:209], v[58:61]
	v_mfma_f32_16x16x32_bf16 v[46:49], v[150:153], v[214:217], v[46:49]
	v_mfma_f32_16x16x32_bf16 v[42:45], v[158:161], v[214:217], v[42:45]
	v_mfma_f32_16x16x32_bf16 v[30:33], v[150:153], v[222:225], v[30:33]
	v_mfma_f32_16x16x32_bf16 v[26:29], v[158:161], v[222:225], v[26:29]
	v_mfma_f32_16x16x32_bf16 v[14:17], v[150:153], v[230:233], v[14:17]
	v_mfma_f32_16x16x32_bf16 v[10:13], v[158:161], v[230:233], v[10:13]
	v_mfma_f32_16x16x32_bf16 v[54:57], v[186:189], v[202:205], 0
	v_mfma_f32_16x16x32_bf16 v[50:53], v[194:197], v[202:205], 0
	v_mfma_f32_16x16x32_bf16 v[38:41], v[186:189], v[210:213], 0
	v_mfma_f32_16x16x32_bf16 v[34:37], v[194:197], v[210:213], 0
	v_mfma_f32_16x16x32_bf16 v[22:25], v[186:189], v[218:221], 0
	v_mfma_f32_16x16x32_bf16 v[18:21], v[194:197], v[218:221], 0
	v_mfma_f32_16x16x32_bf16 v[6:9], v[186:189], v[226:229], 0
	v_mfma_f32_16x16x32_bf16 v[2:5], v[194:197], v[226:229], 0
	v_mfma_f32_16x16x32_bf16 v[54:57], v[190:193], v[206:209], v[54:57]
	v_mfma_f32_16x16x32_bf16 v[50:53], v[198:201], v[206:209], v[50:53]
	v_mfma_f32_16x16x32_bf16 v[38:41], v[190:193], v[214:217], v[38:41]
	v_mfma_f32_16x16x32_bf16 v[34:37], v[198:201], v[214:217], v[34:37]
	v_mfma_f32_16x16x32_bf16 v[22:25], v[190:193], v[222:225], v[22:25]
	v_mfma_f32_16x16x32_bf16 v[18:21], v[198:201], v[222:225], v[18:21]
	v_mfma_f32_16x16x32_bf16 v[6:9], v[190:193], v[230:233], v[6:9]
	v_mfma_f32_16x16x32_bf16 v[2:5], v[198:201], v[230:233], v[2:5]
	s_barrier
; #define PG8_STAGE(bufoff, gbase, off, q) do { \
;         __builtin_amdgcn_global_load_lds((const unsigned*)((const char*)(gbase) + (off)), (LAS unsigned*)(lds + (bufoff) + ldsw), 16, 0, 0); \
;         __builtin_amdgcn_global_load_lds((const unsigned*)((const char*)(gbase) + (q) + (off)), (LAS unsigned*)(lds + (bufoff) + ldsw + 8192), 16, 0, 0); } while (0)
; #define PG8_LDA(dst, b, h) do { _Pragma("unroll") for (int m = 0; m < 4; ++m) _Pragma("unroll") for (int k = 0; k < 2; ++k) dst[m][k] = *(const LAS bf16x8*)(lds + PG8_SA(b, h) + aoff + m * 2048 + k * 1024); } while (0)
; #define PG8_LDB(dst, b, h) do { _Pragma("unroll") for (int n = 0; n < 2; ++n) _Pragma("unroll") for (int k = 0; k < 2; ++k) dst[n][k] = *(const LAS bf16x8*)(lds + PG8_SB(b, h) + boff + n * 2048 + k * 1024); } while (0)
; #define PG8_MMA(ai, bj, At, Bt) do { __builtin_amdgcn_s_setprio(1); _Pragma("unroll") for (int m = 0; m < 4; ++m) _Pragma("unroll") for (int n = 0; n < 2; ++n) _Pragma("unroll") for (int k = 0; k < 2; ++k) \
;         acc[ai][bj][m][n] = __builtin_amdgcn_mfma_f32_16x16x32_bf16(Bt[n][k], At[m][k], acc[ai][bj][m][n], 0, 0, 0); __builtin_amdgcn_s_setprio(0); } while (0)
; #define PG8_WAIT_V(n) asm volatile("s_waitcnt vmcnt(" #n ")" ::: "memory")
; #define PG8_WAIT_L(n) asm volatile("s_waitcnt lgkmcnt(" #n ")" ::: "memory")
; #define PG8_BAR __builtin_amdgcn_s_barrier()
; #define PG8_SCHED __builtin_amdgcn_sched_barrier(0)
; template <class Epi, class Sched>
; __device__ __forceinline__ void gemm_phase(LAS unsigned char* lds, const int tid, const Sched& S, const Epi& E) {
;     ...
;             PG8_LDB(B0, 1, 0); PG8_LDB(B1, 1, 1); PG8_SCHED; PG8_LDA(At, 1, 0); PG8_STAGE(PG8_SA(0, 1), a2 + hA2, oA2, qA2);
;             PG8_WAIT_V(8); PG8_WAIT_L(0); PG8_BAR; PG8_MMA(0, 0, At, B0); PG8_MMA(0, 1, At, B1); PG8_BAR; PG8_SCHED;
;             PG8_LDA(At, 1, 1); PG8_STAGE(PG8_SB(1, 0), b3, oB2, qB2); PG8_STAGE(PG8_SB(1, 1), b3 + hB2, oB2, qB2); PG8_STAGE(PG8_SA(1, 0), a3, oA2, qA2);
;             PG8_WAIT_V(8); PG8_WAIT_L(0); PG8_BAR; PG8_MMA(1, 0, At, B0); PG8_MMA(1, 1, At, B1); PG8_BAR; PG8_SCHED;
;         }
	s_setprio 0
	s_add_i32 s10, 0, 0x18000
	s_add_i32 s11, 0, 0x1c000
	ds_read_b128 v[140:143], v133 offset:32768
	ds_read_b128 v[150:153], v133 offset:33792
	ds_read_b128 v[154:157], v133 offset:34816
	ds_read_b128 v[158:161], v133 offset:35840
	ds_read_b128 v[186:189], v133 offset:49152
	ds_read_b128 v[190:193], v133 offset:50176
	ds_read_b128 v[194:197], v133 offset:51200
	ds_read_b128 v[198:201], v133 offset:52224
	s_add_u32 s6, vcc_lo, s58
	s_addc_u32 s7, vcc_hi, s59
	s_mov_b32 m0, s91
	ds_read_b128 v[202:205], v184 offset:32768
	ds_read_b128 v[206:209], v184 offset:33792
	ds_read_b128 v[210:213], v184 offset:34816
	ds_read_b128 v[214:217], v184 offset:35840
	ds_read_b128 v[218:221], v184 offset:36864
	ds_read_b128 v[222:225], v184 offset:37888
	ds_read_b128 v[226:229], v184 offset:38912
	ds_read_b128 v[230:233], v184 offset:39936
	global_load_lds_dwordx4 v136, s[6:7]
	s_add_u32 s6, s6, s64
	s_addc_u32 s7, s7, s65
	s_mov_b32 m0, s93
	s_nop 0
	global_load_lds_dwordx4 v136, s[6:7]
	s_waitcnt vmcnt(8)
	s_waitcnt lgkmcnt(0)
	s_setprio 1
	s_barrier
	v_mfma_f32_16x16x32_bf16 v[126:129], v[140:143], v[202:205], v[126:129]
	v_mfma_f32_16x16x32_bf16 v[122:125], v[154:157], v[202:205], v[122:125]
	v_mfma_f32_16x16x32_bf16 v[110:113], v[140:143], v[210:213], v[110:113]
	v_mfma_f32_16x16x32_bf16 v[106:109], v[154:157], v[210:213], v[106:109]
	v_mfma_f32_16x16x32_bf16 v[94:97], v[140:143], v[218:221], v[94:97]
	v_mfma_f32_16x16x32_bf16 v[90:93], v[154:157], v[218:221], v[90:93]
	v_mfma_f32_16x16x32_bf16 v[78:81], v[140:143], v[226:229], v[78:81]
	v_mfma_f32_16x16x32_bf16 v[74:77], v[154:157], v[226:229], v[74:77]
	v_mfma_f32_16x16x32_bf16 v[126:129], v[150:153], v[206:209], v[126:129]
	v_mfma_f32_16x16x32_bf16 v[122:125], v[158:161], v[206:209], v[122:125]
	v_mfma_f32_16x16x32_bf16 v[110:113], v[150:153], v[214:217], v[110:113]
	v_mfma_f32_16x16x32_bf16 v[106:109], v[158:161], v[214:217], v[106:109]
	v_mfma_f32_16x16x32_bf16 v[94:97], v[150:153], v[222:225], v[94:97]
	v_mfma_f32_16x16x32_bf16 v[90:93], v[158:161], v[222:225], v[90:93]
	v_mfma_f32_16x16x32_bf16 v[78:81], v[150:153], v[230:233], v[78:81]
	v_mfma_f32_16x16x32_bf16 v[74:77], v[158:161], v[230:233], v[74:77]
	v_mfma_f32_16x16x32_bf16 v[118:121], v[186:189], v[202:205], v[118:121]
	v_mfma_f32_16x16x32_bf16 v[114:117], v[194:197], v[202:205], v[114:117]
	v_mfma_f32_16x16x32_bf16 v[102:105], v[186:189], v[210:213], v[102:105]
	v_mfma_f32_16x16x32_bf16 v[98:101], v[194:197], v[210:213], v[98:101]
	v_mfma_f32_16x16x32_bf16 v[86:89], v[186:189], v[218:221], v[86:89]
	v_mfma_f32_16x16x32_bf16 v[82:85], v[194:197], v[218:221], v[82:85]
	v_mfma_f32_16x16x32_bf16 v[70:73], v[186:189], v[226:229], v[70:73]
	v_mfma_f32_16x16x32_bf16 v[66:69], v[194:197], v[226:229], v[66:69]
	v_mfma_f32_16x16x32_bf16 v[118:121], v[190:193], v[206:209], v[118:121]
	v_mfma_f32_16x16x32_bf16 v[114:117], v[198:201], v[206:209], v[114:117]
	v_mfma_f32_16x16x32_bf16 v[102:105], v[190:193], v[214:217], v[102:105]
	v_mfma_f32_16x16x32_bf16 v[98:101], v[198:201], v[214:217], v[98:101]
	v_mfma_f32_16x16x32_bf16 v[86:89], v[190:193], v[222:225], v[86:89]
	v_mfma_f32_16x16x32_bf16 v[82:85], v[198:201], v[222:225], v[82:85]
	v_mfma_f32_16x16x32_bf16 v[70:73], v[190:193], v[230:233], v[70:73]
	v_mfma_f32_16x16x32_bf16 v[66:69], v[198:201], v[230:233], v[66:69]
	s_barrier
	s_setprio 0
	s_add_i32 s6, s10, s47
	s_add_i32 m0, s6, 0xffffff80
	ds_read_b128 v[202:205], v184 offset:49152
	ds_read_b128 v[206:209], v184 offset:50176
	ds_read_b128 v[210:213], v184 offset:51200
	ds_read_b128 v[214:217], v184 offset:52224
	ds_read_b128 v[218:221], v184 offset:53248
	ds_read_b128 v[222:225], v184 offset:54272
	ds_read_b128 v[226:229], v184 offset:55296
	ds_read_b128 v[230:233], v184 offset:56320
	global_load_lds_dwordx4 v0, s[28:29] offset:128
	s_add_i32 m0, s6, 0x1f80
	s_add_i32 s6, s11, s47
	s_ashr_i32 s100, s73, 31
	s_add_u32 s98, s28, s73
	s_addc_u32 s99, s29, s100
	global_load_lds_dwordx4 v0, s[98:99] offset:128
	s_add_i32 m0, s6, 0xffffff80
	s_nop 0
	s_ashr_i32 s101, s19, 31
	s_add_u32 s98, s28, s19
	s_addc_u32 s99, s29, s101
	global_load_lds_dwordx4 v0, s[98:99] offset:128
	s_add_i32 m0, s6, 0x1f80
	s_nop 0
	s_add_u32 s98, s98, s73
	s_addc_u32 s99, s99, s100
	global_load_lds_dwordx4 v0, s[98:99] offset:128
	s_add_i32 m0, s77, 0xffffff80
	s_nop 0
	global_load_lds_dwordx4 v136, vcc offset:128
	s_add_i32 m0, s88, 0xffffff80
	s_nop 0
	s_add_u32 s98, vcc_lo, s64
	s_addc_u32 s99, vcc_hi, s65
	global_load_lds_dwordx4 v136, s[98:99] offset:128
	s_waitcnt vmcnt(8)
	s_waitcnt lgkmcnt(0)
	s_setprio 1
	s_barrier
	v_mfma_f32_16x16x32_bf16 v[62:65], v[140:143], v[202:205], v[62:65]
	v_mfma_f32_16x16x32_bf16 v[58:61], v[154:157], v[202:205], v[58:61]
	v_mfma_f32_16x16x32_bf16 v[46:49], v[140:143], v[210:213], v[46:49]
	v_mfma_f32_16x16x32_bf16 v[42:45], v[154:157], v[210:213], v[42:45]
	v_mfma_f32_16x16x32_bf16 v[30:33], v[140:143], v[218:221], v[30:33]
	v_mfma_f32_16x16x32_bf16 v[26:29], v[154:157], v[218:221], v[26:29]
	v_mfma_f32_16x16x32_bf16 v[14:17], v[140:143], v[226:229], v[14:17]
	v_mfma_f32_16x16x32_bf16 v[10:13], v[154:157], v[226:229], v[10:13]
	v_mfma_f32_16x16x32_bf16 v[62:65], v[150:153], v[206:209], v[62:65]
	v_mfma_f32_16x16x32_bf16 v[58:61], v[158:161], v[206:209], v[58:61]
	v_mfma_f32_16x16x32_bf16 v[46:49], v[150:153], v[214:217], v[46:49]
	v_mfma_f32_16x16x32_bf16 v[42:45], v[158:161], v[214:217], v[42:45]
	v_mfma_f32_16x16x32_bf16 v[30:33], v[150:153], v[222:225], v[30:33]
	v_mfma_f32_16x16x32_bf16 v[26:29], v[158:161], v[222:225], v[26:29]
	v_mfma_f32_16x16x32_bf16 v[14:17], v[150:153], v[230:233], v[14:17]
	v_mfma_f32_16x16x32_bf16 v[10:13], v[158:161], v[230:233], v[10:13]
	v_mfma_f32_16x16x32_bf16 v[54:57], v[186:189], v[202:205], v[54:57]
	v_mfma_f32_16x16x32_bf16 v[50:53], v[194:197], v[202:205], v[50:53]
	v_mfma_f32_16x16x32_bf16 v[38:41], v[186:189], v[210:213], v[38:41]
	v_mfma_f32_16x16x32_bf16 v[34:37], v[194:197], v[210:213], v[34:37]
	v_mfma_f32_16x16x32_bf16 v[22:25], v[186:189], v[218:221], v[22:25]
	v_mfma_f32_16x16x32_bf16 v[18:21], v[194:197], v[218:221], v[18:21]
	v_mfma_f32_16x16x32_bf16 v[6:9], v[186:189], v[226:229], v[6:9]
	v_mfma_f32_16x16x32_bf16 v[2:5], v[194:197], v[226:229], v[2:5]
	v_mfma_f32_16x16x32_bf16 v[54:57], v[190:193], v[206:209], v[54:57]
	v_mfma_f32_16x16x32_bf16 v[50:53], v[198:201], v[206:209], v[50:53]
	v_mfma_f32_16x16x32_bf16 v[38:41], v[190:193], v[214:217], v[38:41]
	v_mfma_f32_16x16x32_bf16 v[34:37], v[198:201], v[214:217], v[34:37]
	v_mfma_f32_16x16x32_bf16 v[22:25], v[190:193], v[222:225], v[22:25]
	v_mfma_f32_16x16x32_bf16 v[18:21], v[198:201], v[222:225], v[18:21]
	v_mfma_f32_16x16x32_bf16 v[6:9], v[190:193], v[230:233], v[6:9]
	v_mfma_f32_16x16x32_bf16 v[2:5], v[198:201], v[230:233], v[2:5]
	s_barrier
	s_setprio 0
	s_cmp_ge_i32 s20, s37
	s_cbranch_scc1 .LBB0_177
	s_mov_b32 s17, s20
	s_branch .LBB0_173

; #define PG8_STAGE(bufoff, gbase, off, q) do { \
;         __builtin_amdgcn_global_load_lds((const unsigned*)((const char*)(gbase) + (off)), (LAS unsigned*)(lds + (bufoff) + ldsw), 16, 0, 0); \
;         __builtin_amdgcn_global_load_lds((const unsigned*)((const char*)(gbase) + (q) + (off)), (LAS unsigned*)(lds + (bufoff) + ldsw + 8192), 16, 0, 0); } while (0)
; #define PG8_LDA(dst, b, h) do { _Pragma("unroll") for (int m = 0; m < 4; ++m) _Pragma("unroll") for (int k = 0; k < 2; ++k) dst[m][k] = *(const LAS bf16x8*)(lds + PG8_SA(b, h) + aoff + m * 2048 + k * 1024); } while (0)
; #define PG8_LDB(dst, b, h) do { _Pragma("unroll") for (int n = 0; n < 2; ++n) _Pragma("unroll") for (int k = 0; k < 2; ++k) dst[n][k] = *(const LAS bf16x8*)(lds + PG8_SB(b, h) + boff + n * 2048 + k * 1024); } while (0)
; #define PG8_MMA(ai, bj, At, Bt) do { __builtin_amdgcn_s_setprio(1); _Pragma("unroll") for (int m = 0; m < 4; ++m) _Pragma("unroll") for (int n = 0; n < 2; ++n) _Pragma("unroll") for (int k = 0; k < 2; ++k) \
;         acc[ai][bj][m][n] = __builtin_amdgcn_mfma_f32_16x16x32_bf16(Bt[n][k], At[m][k], acc[ai][bj][m][n], 0, 0, 0); __builtin_amdgcn_s_setprio(0); } while (0)
; #define PG8_WAIT_V(n) asm volatile("s_waitcnt vmcnt(" #n ")" ::: "memory")
; #define PG8_WAIT_L(n) asm volatile("s_waitcnt lgkmcnt(" #n ")" ::: "memory")
; #define PG8_BAR __builtin_amdgcn_s_barrier()
; #define PG8_SCHED __builtin_amdgcn_sched_barrier(0)
; template <class Epi, class Sched>
; __device__ __forceinline__ void gemm_phase(LAS unsigned char* lds, const int tid, const Sched& S, const Epi& E) {
;     ...
;             PG8_LDB(B0, 0, 0); PG8_LDB(B1, 0, 1); PG8_SCHED; PG8_LDA(At, 0, 0); PG8_STAGE(PG8_SA(1, 1), a1 + hA, offA, qA);
;             PG8_WAIT_V(8); PG8_WAIT_L(0); PG8_BAR; PG8_MMA(0, 0, At, B0); PG8_MMA(0, 1, At, B1); PG8_BAR; PG8_SCHED;
;             PG8_LDA(At, 0, 1); PG8_STAGE(PG8_SB(0, 0), b2, oB2, qB2); PG8_STAGE(PG8_SB(0, 1), b2 + hB2, oB2, qB2); PG8_STAGE(PG8_SA(0, 0), a2, oA2, qA2);
;             PG8_WAIT_V(8); PG8_WAIT_L(0); PG8_BAR; PG8_MMA(1, 0, At, B0); PG8_MMA(1, 1, At, B1); PG8_BAR; PG8_SCHED;
.Lk0b_175:
	s_or_b32 vcc_lo, s17, 1
	s_mov_b32 vcc_hi, s21
	s_lshl_b64 s[10:11], vcc, 7
	s_add_u32 s17, s40, s6
	s_addc_u32 vcc_lo, s41, s7
	s_and_b64 s[6:7], exec, s[62:63]
	s_cselect_b32 vcc_hi, s82, vcc_lo
	s_cselect_b32 vcc_lo, s48, s17
	s_add_i32 s17, 0, 0x10000
	s_add_i32 s62, 0, 0x14000
	ds_read_b128 v[140:143], v133
	ds_read_b128 v[150:153], v133 offset:1024
	ds_read_b128 v[154:157], v133 offset:2048
	ds_read_b128 v[158:161], v133 offset:3072
	ds_read_b128 v[186:189], v133 offset:16384
	ds_read_b128 v[190:193], v133 offset:17408
	ds_read_b128 v[194:197], v133 offset:18432
	ds_read_b128 v[198:201], v133 offset:19456
	s_add_u32 s6, s68, s10
	s_addc_u32 s7, s16, s11
	s_add_i32 m0, s54, 0xc000
	ds_read_b128 v[202:205], v184
	ds_read_b128 v[206:209], v184 offset:1024
	ds_read_b128 v[210:213], v184 offset:2048
	ds_read_b128 v[214:217], v184 offset:3072
	ds_read_b128 v[218:221], v184 offset:4096
	ds_read_b128 v[222:225], v184 offset:5120
	ds_read_b128 v[226:229], v184 offset:6144
	ds_read_b128 v[230:233], v184 offset:7168
	global_load_lds_dwordx4 v134, s[6:7]
	s_add_u32 s6, s6, s66
	s_addc_u32 s7, s7, s67
	s_add_i32 m0, s54, 0xe000
	s_nop 0
	global_load_lds_dwordx4 v134, s[6:7]
	s_waitcnt vmcnt(24)
	s_waitcnt lgkmcnt(0)
	s_setprio 1
	s_barrier
	v_mfma_f32_16x16x32_bf16 v[126:129], v[140:143], v[202:205], 0
	v_mfma_f32_16x16x32_bf16 v[122:125], v[154:157], v[202:205], 0
	v_mfma_f32_16x16x32_bf16 v[110:113], v[140:143], v[210:213], 0
	v_mfma_f32_16x16x32_bf16 v[106:109], v[154:157], v[210:213], 0
	v_mfma_f32_16x16x32_bf16 v[94:97], v[140:143], v[218:221], 0
	v_mfma_f32_16x16x32_bf16 v[90:93], v[154:157], v[218:221], 0
	v_mfma_f32_16x16x32_bf16 v[78:81], v[140:143], v[226:229], 0
	v_mfma_f32_16x16x32_bf16 v[74:77], v[154:157], v[226:229], 0
	v_mfma_f32_16x16x32_bf16 v[126:129], v[150:153], v[206:209], v[126:129]
	v_mfma_f32_16x16x32_bf16 v[122:125], v[158:161], v[206:209], v[122:125]
	v_mfma_f32_16x16x32_bf16 v[110:113], v[150:153], v[214:217], v[110:113]
	v_mfma_f32_16x16x32_bf16 v[106:109], v[158:161], v[214:217], v[106:109]
	v_mfma_f32_16x16x32_bf16 v[94:97], v[150:153], v[222:225], v[94:97]
	v_mfma_f32_16x16x32_bf16 v[90:93], v[158:161], v[222:225], v[90:93]
	v_mfma_f32_16x16x32_bf16 v[78:81], v[150:153], v[230:233], v[78:81]
	v_mfma_f32_16x16x32_bf16 v[74:77], v[158:161], v[230:233], v[74:77]
	v_mfma_f32_16x16x32_bf16 v[118:121], v[186:189], v[202:205], 0
	v_mfma_f32_16x16x32_bf16 v[114:117], v[194:197], v[202:205], 0
	v_mfma_f32_16x16x32_bf16 v[102:105], v[186:189], v[210:213], 0
	v_mfma_f32_16x16x32_bf16 v[98:101], v[194:197], v[210:213], 0
	v_mfma_f32_16x16x32_bf16 v[86:89], v[186:189], v[218:221], 0
	v_mfma_f32_16x16x32_bf16 v[82:85], v[194:197], v[218:221], 0
	v_mfma_f32_16x16x32_bf16 v[70:73], v[186:189], v[226:229], 0
	v_mfma_f32_16x16x32_bf16 v[66:69], v[194:197], v[226:229], 0
	v_mfma_f32_16x16x32_bf16 v[118:121], v[190:193], v[206:209], v[118:121]
	v_mfma_f32_16x16x32_bf16 v[114:117], v[198:201], v[206:209], v[114:117]
	v_mfma_f32_16x16x32_bf16 v[102:105], v[190:193], v[214:217], v[102:105]
	v_mfma_f32_16x16x32_bf16 v[98:101], v[198:201], v[214:217], v[98:101]
	v_mfma_f32_16x16x32_bf16 v[86:89], v[190:193], v[222:225], v[86:89]
	v_mfma_f32_16x16x32_bf16 v[82:85], v[198:201], v[222:225], v[82:85]
	v_mfma_f32_16x16x32_bf16 v[70:73], v[190:193], v[230:233], v[70:73]
	v_mfma_f32_16x16x32_bf16 v[66:69], v[198:201], v[230:233], v[66:69]
	s_barrier
	s_setprio 0
	s_add_i32 s10, s17, s47
	s_ashr_i32 s11, s73, 31
	s_mov_b32 m0, s10
	s_add_u32 s6, s28, s73
	ds_read_b128 v[202:205], v184 offset:16384
	ds_read_b128 v[206:209], v184 offset:17408
	ds_read_b128 v[210:213], v184 offset:18432
	ds_read_b128 v[214:217], v184 offset:19456
	ds_read_b128 v[218:221], v184 offset:20480
	ds_read_b128 v[222:225], v184 offset:21504
	ds_read_b128 v[226:229], v184 offset:22528
	ds_read_b128 v[230:233], v184 offset:23552
	global_load_lds_dwordx4 v0, s[28:29]
	s_addc_u32 s7, s29, s11
	s_add_i32 m0, s10, 0x2000
	s_nop 0
	global_load_lds_dwordx4 v0, s[6:7]
	s_ashr_i32 s7, s19, 31
	s_add_u32 s6, s28, s19
	s_addc_u32 s7, s29, s7
	s_add_i32 s10, s62, s47
	s_mov_b32 m0, s10
	s_nop 0
	global_load_lds_dwordx4 v0, s[6:7]
	s_add_u32 s6, s6, s73
	s_addc_u32 s7, s7, s11
	s_add_i32 m0, s10, 0x2000
	s_nop 0
	global_load_lds_dwordx4 v0, s[6:7]
	s_add_u32 s6, vcc_lo, s64
	s_mov_b32 m0, s54
	s_addc_u32 s7, vcc_hi, s65
	global_load_lds_dwordx4 v136, vcc
	s_mov_b32 m0, s55
	s_nop 0
	global_load_lds_dwordx4 v136, s[6:7]
	s_waitcnt vmcnt(24)
	s_waitcnt lgkmcnt(0)
	s_setprio 1
	s_barrier
	v_mfma_f32_16x16x32_bf16 v[62:65], v[140:143], v[202:205], 0
	v_mfma_f32_16x16x32_bf16 v[58:61], v[154:157], v[202:205], 0
	v_mfma_f32_16x16x32_bf16 v[46:49], v[140:143], v[210:213], 0
	v_mfma_f32_16x16x32_bf16 v[42:45], v[154:157], v[210:213], 0
	v_mfma_f32_16x16x32_bf16 v[30:33], v[140:143], v[218:221], 0
	v_mfma_f32_16x16x32_bf16 v[26:29], v[154:157], v[218:221], 0
	v_mfma_f32_16x16x32_bf16 v[14:17], v[140:143], v[226:229], 0
	v_mfma_f32_16x16x32_bf16 v[10:13], v[154:157], v[226:229], 0
	v_mfma_f32_16x16x32_bf16 v[62:65], v[150:153], v[206:209], v[62:65]
	v_mfma_f32_16x16x32_bf16 v[58:61], v[158:161], v[206:209], v[58:61]
	v_mfma_f32_16x16x32_bf16 v[46:49], v[150:153], v[214:217], v[46:49]
	v_mfma_f32_16x16x32_bf16 v[42:45], v[158:161], v[214:217], v[42:45]
	v_mfma_f32_16x16x32_bf16 v[30:33], v[150:153], v[222:225], v[30:33]
	v_mfma_f32_16x16x32_bf16 v[26:29], v[158:161], v[222:225], v[26:29]
	v_mfma_f32_16x16x32_bf16 v[14:17], v[150:153], v[230:233], v[14:17]
	v_mfma_f32_16x16x32_bf16 v[10:13], v[158:161], v[230:233], v[10:13]
	v_mfma_f32_16x16x32_bf16 v[54:57], v[186:189], v[202:205], 0
	v_mfma_f32_16x16x32_bf16 v[50:53], v[194:197], v[202:205], 0
	v_mfma_f32_16x16x32_bf16 v[38:41], v[186:189], v[210:213], 0
	v_mfma_f32_16x16x32_bf16 v[34:37], v[194:197], v[210:213], 0
	v_mfma_f32_16x16x32_bf16 v[22:25], v[186:189], v[218:221], 0
	v_mfma_f32_16x16x32_bf16 v[18:21], v[194:197], v[218:221], 0
	v_mfma_f32_16x16x32_bf16 v[6:9], v[186:189], v[226:229], 0
	v_mfma_f32_16x16x32_bf16 v[2:5], v[194:197], v[226:229], 0
	v_mfma_f32_16x16x32_bf16 v[54:57], v[190:193], v[206:209], v[54:57]
	v_mfma_f32_16x16x32_bf16 v[50:53], v[198:201], v[206:209], v[50:53]
	v_mfma_f32_16x16x32_bf16 v[38:41], v[190:193], v[214:217], v[38:41]
	v_mfma_f32_16x16x32_bf16 v[34:37], v[198:201], v[214:217], v[34:37]
	v_mfma_f32_16x16x32_bf16 v[22:25], v[190:193], v[222:225], v[22:25]
	v_mfma_f32_16x16x32_bf16 v[18:21], v[198:201], v[222:225], v[18:21]
	v_mfma_f32_16x16x32_bf16 v[6:9], v[190:193], v[230:233], v[6:9]
	v_mfma_f32_16x16x32_bf16 v[2:5], v[198:201], v[230:233], v[2:5]
	s_barrier
; #define PG8_STAGE(bufoff, gbase, off, q) do { \
;         __builtin_amdgcn_global_load_lds((const unsigned*)((const char*)(gbase) + (off)), (LAS unsigned*)(lds + (bufoff) + ldsw), 16, 0, 0); \
;         __builtin_amdgcn_global_load_lds((const unsigned*)((const char*)(gbase) + (q) + (off)), (LAS unsigned*)(lds + (bufoff) + ldsw + 8192), 16, 0, 0); } while (0)
; #define PG8_LDA(dst, b, h) do { _Pragma("unroll") for (int m = 0; m < 4; ++m) _Pragma("unroll") for (int k = 0; k < 2; ++k) dst[m][k] = *(const LAS bf16x8*)(lds + PG8_SA(b, h) + aoff + m * 2048 + k * 1024); } while (0)
; #define PG8_LDB(dst, b, h) do { _Pragma("unroll") for (int n = 0; n < 2; ++n) _Pragma("unroll") for (int k = 0; k < 2; ++k) dst[n][k] = *(const LAS bf16x8*)(lds + PG8_SB(b, h) + boff + n * 2048 + k * 1024); } while (0)
; #define PG8_MMA(ai, bj, At, Bt) do { __builtin_amdgcn_s_setprio(1); _Pragma("unroll") for (int m = 0; m < 4; ++m) _Pragma("unroll") for (int n = 0; n < 2; ++n) _Pragma("unroll") for (int k = 0; k < 2; ++k) \
;         acc[ai][bj][m][n] = __builtin_amdgcn_mfma_f32_16x16x32_bf16(Bt[n][k], At[m][k], acc[ai][bj][m][n], 0, 0, 0); __builtin_amdgcn_s_setprio(0); } while (0)
; #define PG8_WAIT_V(n) asm volatile("s_waitcnt vmcnt(" #n ")" ::: "memory")
; #define PG8_WAIT_L(n) asm volatile("s_waitcnt lgkmcnt(" #n ")" ::: "memory")
; #define PG8_BAR __builtin_amdgcn_s_barrier()
; #define PG8_SCHED __builtin_amdgcn_sched_barrier(0)
; template <class Epi, class Sched>
; __device__ __forceinline__ void gemm_phase(LAS unsigned char* lds, const int tid, const Sched& S, const Epi& E) {
;     ...
;             PG8_LDB(B0, 1, 0); PG8_LDB(B1, 1, 1); PG8_SCHED; PG8_LDA(At, 1, 0); PG8_STAGE(PG8_SA(0, 1), a2 + hA2, oA2, qA2);
;             PG8_WAIT_V(8); PG8_WAIT_L(0); PG8_BAR; PG8_MMA(0, 0, At, B0); PG8_MMA(0, 1, At, B1); PG8_BAR; PG8_SCHED;
;             PG8_LDA(At, 1, 1); PG8_STAGE(PG8_SB(1, 0), b3, oB2, qB2); PG8_STAGE(PG8_SB(1, 1), b3 + hB2, oB2, qB2); PG8_STAGE(PG8_SA(1, 0), a3, oA2, qA2);
;             PG8_WAIT_V(8); PG8_WAIT_L(0); PG8_BAR; PG8_MMA(1, 0, At, B0); PG8_MMA(1, 1, At, B1); PG8_BAR; PG8_SCHED;
;         }
	s_setprio 0
	s_add_i32 s10, 0, 0x18000
	s_add_i32 s11, 0, 0x1c000
	ds_read_b128 v[140:143], v133 offset:32768
	ds_read_b128 v[150:153], v133 offset:33792
	ds_read_b128 v[154:157], v133 offset:34816
	ds_read_b128 v[158:161], v133 offset:35840
	ds_read_b128 v[186:189], v133 offset:49152
	ds_read_b128 v[190:193], v133 offset:50176
	ds_read_b128 v[194:197], v133 offset:51200
	ds_read_b128 v[198:201], v133 offset:52224
	s_add_u32 s6, vcc_lo, s58
	s_addc_u32 s7, vcc_hi, s59
	s_mov_b32 m0, s91
	ds_read_b128 v[202:205], v184 offset:32768
	ds_read_b128 v[206:209], v184 offset:33792
	ds_read_b128 v[210:213], v184 offset:34816
	ds_read_b128 v[214:217], v184 offset:35840
	ds_read_b128 v[218:221], v184 offset:36864
	ds_read_b128 v[222:225], v184 offset:37888
	ds_read_b128 v[226:229], v184 offset:38912
	ds_read_b128 v[230:233], v184 offset:39936
	global_load_lds_dwordx4 v136, s[6:7]
	s_add_u32 s6, s6, s64
	s_addc_u32 s7, s7, s65
	s_mov_b32 m0, s93
	s_nop 0
	global_load_lds_dwordx4 v136, s[6:7]
	s_waitcnt vmcnt(8)
	s_waitcnt lgkmcnt(0)
	s_setprio 1
	s_barrier
	v_mfma_f32_16x16x32_bf16 v[126:129], v[140:143], v[202:205], v[126:129]
	v_mfma_f32_16x16x32_bf16 v[122:125], v[154:157], v[202:205], v[122:125]
	v_mfma_f32_16x16x32_bf16 v[110:113], v[140:143], v[210:213], v[110:113]
	v_mfma_f32_16x16x32_bf16 v[106:109], v[154:157], v[210:213], v[106:109]
	v_mfma_f32_16x16x32_bf16 v[94:97], v[140:143], v[218:221], v[94:97]
	v_mfma_f32_16x16x32_bf16 v[90:93], v[154:157], v[218:221], v[90:93]
	v_mfma_f32_16x16x32_bf16 v[78:81], v[140:143], v[226:229], v[78:81]
	v_mfma_f32_16x16x32_bf16 v[74:77], v[154:157], v[226:229], v[74:77]
	v_mfma_f32_16x16x32_bf16 v[126:129], v[150:153], v[206:209], v[126:129]
	v_mfma_f32_16x16x32_bf16 v[122:125], v[158:161], v[206:209], v[122:125]
	v_mfma_f32_16x16x32_bf16 v[110:113], v[150:153], v[214:217], v[110:113]
	v_mfma_f32_16x16x32_bf16 v[106:109], v[158:161], v[214:217], v[106:109]
	v_mfma_f32_16x16x32_bf16 v[94:97], v[150:153], v[222:225], v[94:97]
	v_mfma_f32_16x16x32_bf16 v[90:93], v[158:161], v[222:225], v[90:93]
	v_mfma_f32_16x16x32_bf16 v[78:81], v[150:153], v[230:233], v[78:81]
	v_mfma_f32_16x16x32_bf16 v[74:77], v[158:161], v[230:233], v[74:77]
	v_mfma_f32_16x16x32_bf16 v[118:121], v[186:189], v[202:205], v[118:121]
	v_mfma_f32_16x16x32_bf16 v[114:117], v[194:197], v[202:205], v[114:117]
	v_mfma_f32_16x16x32_bf16 v[102:105], v[186:189], v[210:213], v[102:105]
	v_mfma_f32_16x16x32_bf16 v[98:101], v[194:197], v[210:213], v[98:101]
	v_mfma_f32_16x16x32_bf16 v[86:89], v[186:189], v[218:221], v[86:89]
	v_mfma_f32_16x16x32_bf16 v[82:85], v[194:197], v[218:221], v[82:85]
	v_mfma_f32_16x16x32_bf16 v[70:73], v[186:189], v[226:229], v[70:73]
	v_mfma_f32_16x16x32_bf16 v[66:69], v[194:197], v[226:229], v[66:69]
	v_mfma_f32_16x16x32_bf16 v[118:121], v[190:193], v[206:209], v[118:121]
	v_mfma_f32_16x16x32_bf16 v[114:117], v[198:201], v[206:209], v[114:117]
	v_mfma_f32_16x16x32_bf16 v[102:105], v[190:193], v[214:217], v[102:105]
	v_mfma_f32_16x16x32_bf16 v[98:101], v[198:201], v[214:217], v[98:101]
	v_mfma_f32_16x16x32_bf16 v[86:89], v[190:193], v[222:225], v[86:89]
	v_mfma_f32_16x16x32_bf16 v[82:85], v[198:201], v[222:225], v[82:85]
	v_mfma_f32_16x16x32_bf16 v[70:73], v[190:193], v[230:233], v[70:73]
	v_mfma_f32_16x16x32_bf16 v[66:69], v[198:201], v[230:233], v[66:69]
	s_barrier
	s_setprio 0
	s_add_i32 s6, s10, s47
	s_add_i32 m0, s6, 0xffffff80
	ds_read_b128 v[202:205], v184 offset:49152
	ds_read_b128 v[206:209], v184 offset:50176
	ds_read_b128 v[210:213], v184 offset:51200
	ds_read_b128 v[214:217], v184 offset:52224
	ds_read_b128 v[218:221], v184 offset:53248
	ds_read_b128 v[222:225], v184 offset:54272
	ds_read_b128 v[226:229], v184 offset:55296
	ds_read_b128 v[230:233], v184 offset:56320
	global_load_lds_dwordx4 v0, s[28:29] offset:128
	s_add_i32 m0, s6, 0x1f80
	s_add_i32 s6, s11, s47
	s_ashr_i32 s100, s73, 31
	s_add_u32 s98, s28, s73
	s_addc_u32 s99, s29, s100
	global_load_lds_dwordx4 v0, s[98:99] offset:128
	s_add_i32 m0, s6, 0xffffff80
	s_nop 0
	s_ashr_i32 s101, s19, 31
	s_add_u32 s98, s28, s19
	s_addc_u32 s99, s29, s101
	global_load_lds_dwordx4 v0, s[98:99] offset:128
	s_add_i32 m0, s6, 0x1f80
	s_nop 0
	s_add_u32 s98, s98, s73
	s_addc_u32 s99, s99, s100
	global_load_lds_dwordx4 v0, s[98:99] offset:128
	s_add_i32 m0, s77, 0xffffff80
	s_nop 0
	global_load_lds_dwordx4 v136, vcc offset:128
	s_add_i32 m0, s88, 0xffffff80
	s_nop 0
	s_add_u32 s98, vcc_lo, s64
	s_addc_u32 s99, vcc_hi, s65
	global_load_lds_dwordx4 v136, s[98:99] offset:128
	s_waitcnt vmcnt(8)
	s_waitcnt lgkmcnt(0)
	s_setprio 1
	s_barrier
	v_mfma_f32_16x16x32_bf16 v[62:65], v[140:143], v[202:205], v[62:65]
	v_mfma_f32_16x16x32_bf16 v[58:61], v[154:157], v[202:205], v[58:61]
	v_mfma_f32_16x16x32_bf16 v[46:49], v[140:143], v[210:213], v[46:49]
	v_mfma_f32_16x16x32_bf16 v[42:45], v[154:157], v[210:213], v[42:45]
	v_mfma_f32_16x16x32_bf16 v[30:33], v[140:143], v[218:221], v[30:33]
	v_mfma_f32_16x16x32_bf16 v[26:29], v[154:157], v[218:221], v[26:29]
	v_mfma_f32_16x16x32_bf16 v[14:17], v[140:143], v[226:229], v[14:17]
	v_mfma_f32_16x16x32_bf16 v[10:13], v[154:157], v[226:229], v[10:13]
	v_mfma_f32_16x16x32_bf16 v[62:65], v[150:153], v[206:209], v[62:65]
	v_mfma_f32_16x16x32_bf16 v[58:61], v[158:161], v[206:209], v[58:61]
	v_mfma_f32_16x16x32_bf16 v[46:49], v[150:153], v[214:217], v[46:49]
	v_mfma_f32_16x16x32_bf16 v[42:45], v[158:161], v[214:217], v[42:45]
	v_mfma_f32_16x16x32_bf16 v[30:33], v[150:153], v[222:225], v[30:33]
	v_mfma_f32_16x16x32_bf16 v[26:29], v[158:161], v[222:225], v[26:29]
	v_mfma_f32_16x16x32_bf16 v[14:17], v[150:153], v[230:233], v[14:17]
	v_mfma_f32_16x16x32_bf16 v[10:13], v[158:161], v[230:233], v[10:13]
	v_mfma_f32_16x16x32_bf16 v[54:57], v[186:189], v[202:205], v[54:57]
	v_mfma_f32_16x16x32_bf16 v[50:53], v[194:197], v[202:205], v[50:53]
	v_mfma_f32_16x16x32_bf16 v[38:41], v[186:189], v[210:213], v[38:41]
	v_mfma_f32_16x16x32_bf16 v[34:37], v[194:197], v[210:213], v[34:37]
	v_mfma_f32_16x16x32_bf16 v[22:25], v[186:189], v[218:221], v[22:25]
	v_mfma_f32_16x16x32_bf16 v[18:21], v[194:197], v[218:221], v[18:21]
	v_mfma_f32_16x16x32_bf16 v[6:9], v[186:189], v[226:229], v[6:9]
	v_mfma_f32_16x16x32_bf16 v[2:5], v[194:197], v[226:229], v[2:5]
	v_mfma_f32_16x16x32_bf16 v[54:57], v[190:193], v[206:209], v[54:57]
	v_mfma_f32_16x16x32_bf16 v[50:53], v[198:201], v[206:209], v[50:53]
	v_mfma_f32_16x16x32_bf16 v[38:41], v[190:193], v[214:217], v[38:41]
	v_mfma_f32_16x16x32_bf16 v[34:37], v[198:201], v[214:217], v[34:37]
	v_mfma_f32_16x16x32_bf16 v[22:25], v[190:193], v[222:225], v[22:25]
	v_mfma_f32_16x16x32_bf16 v[18:21], v[198:201], v[222:225], v[18:21]
	v_mfma_f32_16x16x32_bf16 v[6:9], v[190:193], v[230:233], v[6:9]
	v_mfma_f32_16x16x32_bf16 v[2:5], v[198:201], v[230:233], v[2:5]
	s_barrier
	s_setprio 0
	s_cmp_ge_i32 s20, s37
	s_cbranch_scc1 .LBB0_177
	s_mov_b32 s17, s20
	s_branch .LBB0_173
